# K/V projection ring of 6 slots instead of 8
# speedup vs baseline: 1.0138x; 1.0005x over previous
; template <int N> DI void wait_vm() { asm volatile("s_waitcnt vmcnt(%0)" ::"n"(N) : "memory"); }
; DI void raw_barrier() { asm volatile("" ::: "memory"); __builtin_amdgcn_s_barrier(); asm volatile("" ::: "memory"); }
;     ...
;     auto issue_one = [&](int kt, int b, int i) {
;         const int row = lrow + 128 * i;
;         if ((NCH % 512 == 0) || (i < NCH / 512) || row < ROWS) {
;             const int kq = (kt + koff) & (KT - 1);
;             const char* ua = (const char*)A + (size_t)((DBG & 1) ? 0 : kq) * (BM * 64);
;             const char* ub = (const char*)Bt + (size_t)((DBG & 2) ? 0 : kq) * ((size_t)ldbk * 2);
;             const char* src;
;             if (BM % 128 == 0) src = (i < BM / 128) ? (ua + i * 8192 + loff) : (ub + (i * 128 - BM) * 64 + loff);
;             else if (i == 0) src = (lrow < BM) ? (ua + loff) : (ub + loff - BM * 64);
;             else src = ub + (i * 128 - BM) * 64 + loff;
;             __builtin_amdgcn_global_load_lds((const unsigned*)src, (unsigned*)(lds + b * BUF + i * 8192 + tid * 16), 16, 0, 0);
;         }
;     };
;     auto issue = [&](int kt, int b) {
; #pragma unroll
;         for (int i = 0; i < NIT; ++i) issue_one(kt, b, i);
;     };
;     ...
;     __syncthreads();
; #pragma unroll
;     for (int d = 0; d < D; ++d) issue(d, d);
;     int cb = 0, ib = D;
;     for (int kt = 0; kt < KT; ++kt) {
;         if (D > 1 && kt + D - 1 < KT) wait_vm<(D - 1) * NIT>(); else wait_vm<0>();
;         raw_barrier();
;         compute(cb, kt + D < KT, kt + D, ib);
.LBB0_859:
	s_andn2_b64 vcc, exec, s[6:7]
	s_cbranch_vccnz .LBB0_891
	s_bfe_u32 s0, s2, 0x50002
	s_lshr_b32 s1, s3, 7
	s_and_b32 s3, s2, 3
	s_lshl_b32 s6, s0, 18
	v_readlane_b32 s7, v244, 38
	v_mov_b32_e32 v44, v212
	s_add_u32 s8, s7, s6
	v_readlane_b32 s6, v244, 39
	v_mov_b32_e32 v4, v212
	s_addc_u32 s9, s6, 0
	s_lshl_b32 s6, s1, 20
	v_readlane_b32 s7, v243, 18
	s_add_u32 s7, s7, s6
	v_lshrrev_b32_e32 v0, 4, v4
	v_readlane_b32 s10, v243, 19
	v_sub_u32_e32 v0, 0, v0
	s_addc_u32 s11, s10, 0
	s_lshl_b32 s10, s3, 13
	v_xor_b32_e32 v0, v4, v0
	v_lshlrev_b32_e32 v5, 4, v4
	s_add_u32 s10, s7, s10
	v_and_b32_e32 v2, 0xffffffc0, v5
	v_lshlrev_b32_e32 v0, 4, v0
	s_addc_u32 s11, s11, 0
	v_and_or_b32 v0, v0, 48, v2
	v_lshl_add_u64 v[34:35], s[8:9], 0, v[0:1]
	v_lshl_add_u64 v[36:37], s[10:11], 0, v[0:1]
	v_readlane_b32 s8, v243, 25
	v_add_u32_e32 v0, 0, v5
	v_readlane_b32 s9, v243, 26
	v_readfirstlane_b32 s7, v0
	v_add_u32_e32 v5, 0x2000, v0
	v_lshl_add_u64 v[2:3], v[34:35], 0, s[8:9]
	s_mov_b32 m0, s7
	v_readfirstlane_b32 s7, v5
	v_readlane_b32 s8, v243, 5
	s_waitcnt lgkmcnt(0)
	s_barrier
	global_load_lds_dwordx4 v[2:3], off
	v_lshl_add_u64 v[2:3], v[36:37], 0, s[74:75]
	s_mov_b32 m0, s7
	v_readlane_b32 s9, v243, 6
	v_add_u32_e32 v5, 0x4000, v0
	global_load_lds_dwordx4 v[2:3], off
	v_lshl_add_u64 v[2:3], v[34:35], 0, s[8:9]
	v_readfirstlane_b32 s7, v5
	v_readlane_b32 s8, v243, 20
	v_add_u32_e32 v5, 0x6000, v0
	s_mov_b32 m0, s7
	v_readlane_b32 s9, v243, 21
	v_readfirstlane_b32 s7, v5
	global_load_lds_dwordx4 v[2:3], off
	v_lshl_add_u64 v[2:3], v[36:37], 0, s[8:9]
	s_mov_b32 m0, s7
	v_lshlrev_b32_e32 v5, 2, v4
	global_load_lds_dwordx4 v[2:3], off
	v_ashrrev_i32_e32 v2, 6, v4
	v_lshrrev_b32_e32 v3, 30, v2
	v_add_u32_e32 v3, v2, v3
	v_and_b32_e32 v5, 48, v5
	v_ashrrev_i32_e32 v3, 2, v3
	v_sub_u32_e32 v5, 0, v5
	v_mul_i32_i24_e32 v6, 4, v3
	v_bitop3_b32 v5, v4, 48, v5 bitop3:0x48
	v_lshlrev_b32_e32 v4, 6, v4
	v_sub_u32_e32 v2, v2, v6
	v_and_b32_e32 v4, 0x3c0, v4
	v_lshl_or_b32 v40, v2, 11, v4
	v_mov_b32_e32 v2, 0
	s_mov_b32 s9, 2
	s_mov_b32 s7, 0
	v_add_u32_e32 v38, 0, v5
	v_lshl_or_b32 v39, v3, 12, v4
	v_readlane_b32 s8, v243, 27
	s_mov_b32 s10, 0
	v_mov_b32_e32 v3, v2
	v_mov_b32_e32 v4, v2
	v_mov_b32_e32 v5, v2
	v_mov_b32_e32 v6, v2
	v_mov_b32_e32 v7, v2
	v_mov_b32_e32 v8, v2
	v_mov_b32_e32 v9, v2
	v_mov_b32_e32 v10, v2
	v_mov_b32_e32 v11, v2
	v_mov_b32_e32 v12, v2
	v_mov_b32_e32 v13, v2
	v_mov_b32_e32 v14, v2
	v_mov_b32_e32 v15, v2
	v_mov_b32_e32 v16, v2
	v_mov_b32_e32 v17, v2
	v_mov_b32_e32 v18, v2
	v_mov_b32_e32 v19, v2
	v_mov_b32_e32 v20, v2
	v_mov_b32_e32 v21, v2
	v_mov_b32_e32 v22, v2
	v_mov_b32_e32 v23, v2
	v_mov_b32_e32 v24, v2
	v_mov_b32_e32 v25, v2
	v_mov_b32_e32 v26, v2
	v_mov_b32_e32 v27, v2
	v_mov_b32_e32 v28, v2
	v_mov_b32_e32 v29, v2
	v_mov_b32_e32 v30, v2
	v_mov_b32_e32 v31, v2
	v_mov_b32_e32 v32, v2
	v_mov_b32_e32 v33, v2
	v_readfirstlane_b32 s90, v212
	s_nop 3
	s_cmp_lt_u32 s90, 0x100
	s_cbranch_scc0 .Lpkv_c_entry
	v_readfirstlane_b32 s94, v34
	v_readfirstlane_b32 s95, v35
	v_readfirstlane_b32 s92, v36
	v_readfirstlane_b32 s93, v37
	s_nop 3
	s_lshl_b32 s8, s90, 5
	s_lshl_b32 s40, s90, 4
	v_subrev_u32_e32 v227, s94, v34
	v_add_u32_e32 v227, s8, v227
	s_sub_u32 vcc_lo, s94, s40
	s_subb_u32 vcc_hi, s95, 0
	s_sub_u32 s92, s92, s40
	s_subb_u32 s93, s93, 0
	s_mov_b32 s7, 4
	s_mov_b32 s9, 2
	s_lshl_b32 s94, s9, 14
	s_add_u32 s94, s94, s8
	s_mov_b32 m0, s94
	s_add_i32 s40, s59, s7
	s_and_b32 s40, s40, 62
	s_lshl_b32 s94, s40, 12
	s_add_u32 s94, vcc_lo, s94
	s_addc_u32 s95, vcc_hi, 0
	s_lshl_b32 s40, s40, 14
	global_load_lds_dwordx4 v227, s[94:95]
	global_load_lds_dwordx4 v227, s[94:95] offset:1024
	s_add_u32 s94, s92, s40
	s_addc_u32 s95, s93, 0
	s_add_u32 m0, m0, 0x2000
	s_nop 0
	global_load_lds_dwordx4 v227, s[94:95]
	global_load_lds_dwordx4 v227, s[94:95] offset:1024
	s_mov_b32 s7, 6
	s_mov_b32 s9, 3
	s_lshl_b32 s94, s9, 14
	s_add_u32 s94, s94, s8
	s_mov_b32 m0, s94
	s_add_i32 s40, s59, s7
	s_and_b32 s40, s40, 62
	s_lshl_b32 s94, s40, 12
	s_add_u32 s94, vcc_lo, s94
	s_addc_u32 s95, vcc_hi, 0
	s_lshl_b32 s40, s40, 14
	global_load_lds_dwordx4 v227, s[94:95]
	global_load_lds_dwordx4 v227, s[94:95] offset:1024
	s_add_u32 s94, s92, s40
	s_addc_u32 s95, s93, 0
	s_add_u32 m0, m0, 0x2000
	s_nop 0
	global_load_lds_dwordx4 v227, s[94:95]
	global_load_lds_dwordx4 v227, s[94:95] offset:1024
	s_mov_b32 s7, 8
	s_mov_b32 s9, 4
	s_lshl_b32 s94, s9, 14
	s_add_u32 s94, s94, s8
	s_mov_b32 m0, s94
	s_add_i32 s40, s59, s7
	s_and_b32 s40, s40, 62
	s_lshl_b32 s94, s40, 12
	s_add_u32 s94, vcc_lo, s94
	s_addc_u32 s95, vcc_hi, 0
	s_lshl_b32 s40, s40, 14
	global_load_lds_dwordx4 v227, s[94:95]
	global_load_lds_dwordx4 v227, s[94:95] offset:1024
	s_add_u32 s94, s92, s40
	s_addc_u32 s95, s93, 0
	s_add_u32 m0, m0, 0x2000
	s_nop 0
	global_load_lds_dwordx4 v227, s[94:95]
	global_load_lds_dwordx4 v227, s[94:95] offset:1024
	s_mov_b32 s7, 10
	s_mov_b32 s9, 5
	s_lshl_b32 s94, s9, 14
	s_add_u32 s94, s94, s8
	s_mov_b32 m0, s94
	s_add_i32 s40, s59, s7
	s_and_b32 s40, s40, 62
	s_lshl_b32 s94, s40, 12
	s_add_u32 s94, vcc_lo, s94
	s_addc_u32 s95, vcc_hi, 0
	s_lshl_b32 s40, s40, 14
	global_load_lds_dwordx4 v227, s[94:95]
	global_load_lds_dwordx4 v227, s[94:95] offset:1024
	s_add_u32 s94, s92, s40
	s_addc_u32 s95, s93, 0
	s_add_u32 m0, m0, 0x2000
	s_nop 0
	global_load_lds_dwordx4 v227, s[94:95]
	global_load_lds_dwordx4 v227, s[94:95] offset:1024
	s_mov_b32 s7, 12
	s_mov_b32 s9, 0
	s_mov_b32 s10, 1
	s_waitcnt vmcnt(18)
	s_barrier
	v_add_u32_e32 v225, v38, v40
	v_add_u32_e32 v224, v38, v39
	ds_read_b128 v[54:57], v224
	ds_read_b128 v[58:61], v224 offset:1024
	ds_read_b128 v[62:65], v224 offset:2048
	ds_read_b128 v[46:49], v225 offset:8192
	ds_read_b128 v[50:53], v225 offset:9216
	ds_read_b128 v[216:219], v224 offset:3072
; DI f32x4 mfma16(bf16x8 a, bf16x8 b, f32x4 c) { return __builtin_amdgcn_mfma_f32_16x16x32_bf16(a, b, c, 0, 0, 0); }
; template <int N> DI void wait_vm() { asm volatile("s_waitcnt vmcnt(%0)" ::"n"(N) : "memory"); }
; DI void raw_barrier() { asm volatile("" ::: "memory"); __builtin_amdgcn_s_barrier(); asm volatile("" ::: "memory"); }
;     ...
;     auto compute = [&](int cb, bool do_issue, int ikt, int ib) {
;         const char* base = lds + cb * BUF;
;         bf16x8 af[MT], bfr[NT];
; #pragma unroll
;         for (int nt = 0; nt < NT; ++nt) {
;             const int br = BM + (nt / NTS) * (BN / NSEG) + wc * (NTS * 16) + (nt % NTS) * 16;
;             bfr[nt] = *(const bf16x8*)(base + (br + l15) * 64 + rsw);
;         }
; #pragma unroll
;         for (int mt = 0; mt < MT; ++mt) af[mt] = *(const bf16x8*)(base + (wr * WM + mt * 16 + l15) * 64 + rsw);
;         constexpr int TOT = MT * NT, PER = (TOT + NIT - 1) / NIT;
; #pragma unroll
;         for (int part = 0; part < NIT; ++part) {
; #pragma unroll
;             for (int q = 0; q < PER; ++q) {
;                 const int idx = part * PER + q;
;                 if (idx < TOT) {
;                     const int mt = idx / NT, nt = idx % NT;
;                     acc[mt][nt] = SWAP ? mfma16(bfr[nt], af[mt], acc[mt][nt]) : mfma16(af[mt], bfr[nt], acc[mt][nt]);
;                 }
;             }
;             __builtin_amdgcn_sched_barrier(0);
;             if (do_issue) issue_one(ikt, ib, part);
;             __builtin_amdgcn_sched_barrier(0);
;         }
;     };
;     __syncthreads();
; #pragma unroll
;     for (int d = 0; d < D; ++d) issue(d, d);
;     int cb = 0, ib = D;
;     for (int kt = 0; kt < KT; ++kt) {
;         if (D > 1 && kt + D - 1 < KT) wait_vm<(D - 1) * NIT>(); else wait_vm<0>();
;         raw_barrier();
;         compute(cb, kt + D < KT, kt + D, ib);
;         cb = (cb + 1 == NST) ? 0 : cb + 1;
;         ib = (ib + 1 == NST) ? 0 : ib + 1;
.Lpkv_l_loop:
	s_lshl_b32 s94, s10, 14
	v_add_u32_e32 v226, s94, v38
	v_add_u32_e32 v225, v226, v40
	v_add_u32_e32 v224, v226, v39
	s_waitcnt lgkmcnt(2)
	v_mfma_f32_16x16x32_bf16 v[30:33], v[46:49], v[54:57], v[30:33]
	s_waitcnt lgkmcnt(1)
	v_mfma_f32_16x16x32_bf16 v[26:29], v[50:53], v[54:57], v[26:29]
	s_waitcnt vmcnt(16) lgkmcnt(0)
	s_barrier
	ds_read_b128 v[54:57], v224
	s_lshl_b32 s94, s9, 14
	s_add_u32 s94, s94, s8
	s_mov_b32 m0, s94
	s_add_i32 s40, s59, s7
	s_and_b32 s40, s40, 62
	s_lshl_b32 s94, s40, 12
	s_add_u32 s94, vcc_lo, s94
	s_addc_u32 s95, vcc_hi, 0
	s_lshl_b32 s40, s40, 14
	global_load_lds_dwordx4 v227, s[94:95]
	global_load_lds_dwordx4 v227, s[94:95] offset:1024
	v_mfma_f32_16x16x32_bf16 v[22:25], v[46:49], v[58:61], v[22:25]
	v_mfma_f32_16x16x32_bf16 v[18:21], v[50:53], v[58:61], v[18:21]
	s_add_u32 s94, s92, s40
	s_addc_u32 s95, s93, 0
	s_add_u32 m0, m0, 0x2000
	s_nop 0
	global_load_lds_dwordx4 v227, s[94:95]
	global_load_lds_dwordx4 v227, s[94:95] offset:1024
	ds_read_b128 v[58:61], v224 offset:1024
	v_mfma_f32_16x16x32_bf16 v[14:17], v[46:49], v[62:65], v[14:17]
	v_mfma_f32_16x16x32_bf16 v[10:13], v[50:53], v[62:65], v[10:13]
	ds_read_b128 v[62:65], v224 offset:2048
	v_mfma_f32_16x16x32_bf16 v[6:9], v[46:49], v[216:219], v[6:9]
	ds_read_b128 v[46:49], v225 offset:8192
	v_mfma_f32_16x16x32_bf16 v[2:5], v[50:53], v[216:219], v[2:5]
	ds_read_b128 v[50:53], v225 offset:9216
	ds_read_b128 v[216:219], v224 offset:3072
	s_add_i32 s10, s10, 1
	s_cmp_lg_u32 s10, 6
	s_cselect_b32 s10, s10, 0
	s_add_i32 s9, s9, 1
	s_cmp_lg_u32 s9, 6
	s_cselect_b32 s9, s9, 0
	s_add_i32 s7, s7, 2
	s_cmp_lg_u32 s7, 64
	s_cbranch_scc1 .Lpkv_l_loop
	s_lshl_b32 s94, s10, 14
	v_add_u32_e32 v226, s94, v38
	v_add_u32_e32 v225, v226, v40
	v_add_u32_e32 v224, v226, v39
	s_waitcnt lgkmcnt(2)
	v_mfma_f32_16x16x32_bf16 v[30:33], v[46:49], v[54:57], v[30:33]
	s_waitcnt lgkmcnt(1)
	v_mfma_f32_16x16x32_bf16 v[26:29], v[50:53], v[54:57], v[26:29]
	s_waitcnt vmcnt(16) lgkmcnt(0)
	s_barrier
	ds_read_b128 v[54:57], v224
	v_mfma_f32_16x16x32_bf16 v[22:25], v[46:49], v[58:61], v[22:25]
	v_mfma_f32_16x16x32_bf16 v[18:21], v[50:53], v[58:61], v[18:21]
	ds_read_b128 v[58:61], v224 offset:1024
	v_mfma_f32_16x16x32_bf16 v[14:17], v[46:49], v[62:65], v[14:17]
	v_mfma_f32_16x16x32_bf16 v[10:13], v[50:53], v[62:65], v[10:13]
	ds_read_b128 v[62:65], v224 offset:2048
	v_mfma_f32_16x16x32_bf16 v[6:9], v[46:49], v[216:219], v[6:9]
	ds_read_b128 v[46:49], v225 offset:8192
	v_mfma_f32_16x16x32_bf16 v[2:5], v[50:53], v[216:219], v[2:5]
	ds_read_b128 v[50:53], v225 offset:9216
	ds_read_b128 v[216:219], v224 offset:3072
	s_add_i32 s10, s10, 1
	s_cmp_lg_u32 s10, 6
	s_cselect_b32 s10, s10, 0
	s_lshl_b32 s94, s10, 14
	v_add_u32_e32 v226, s94, v38
	v_add_u32_e32 v225, v226, v40
	v_add_u32_e32 v224, v226, v39
	s_waitcnt lgkmcnt(2)
	v_mfma_f32_16x16x32_bf16 v[30:33], v[46:49], v[54:57], v[30:33]
	s_waitcnt lgkmcnt(1)
	v_mfma_f32_16x16x32_bf16 v[26:29], v[50:53], v[54:57], v[26:29]
	s_waitcnt vmcnt(12) lgkmcnt(0)
	s_barrier
	ds_read_b128 v[54:57], v224
	v_mfma_f32_16x16x32_bf16 v[22:25], v[46:49], v[58:61], v[22:25]
	v_mfma_f32_16x16x32_bf16 v[18:21], v[50:53], v[58:61], v[18:21]
	ds_read_b128 v[58:61], v224 offset:1024
	v_mfma_f32_16x16x32_bf16 v[14:17], v[46:49], v[62:65], v[14:17]
	v_mfma_f32_16x16x32_bf16 v[10:13], v[50:53], v[62:65], v[10:13]
	ds_read_b128 v[62:65], v224 offset:2048
	v_mfma_f32_16x16x32_bf16 v[6:9], v[46:49], v[216:219], v[6:9]
	ds_read_b128 v[46:49], v225 offset:8192
	v_mfma_f32_16x16x32_bf16 v[2:5], v[50:53], v[216:219], v[2:5]
	ds_read_b128 v[50:53], v225 offset:9216
	ds_read_b128 v[216:219], v224 offset:3072
	s_add_i32 s10, s10, 1
	s_cmp_lg_u32 s10, 6
	s_cselect_b32 s10, s10, 0
	s_lshl_b32 s94, s10, 14
	v_add_u32_e32 v226, s94, v38
	v_add_u32_e32 v225, v226, v40
	v_add_u32_e32 v224, v226, v39
	s_waitcnt lgkmcnt(2)
	v_mfma_f32_16x16x32_bf16 v[30:33], v[46:49], v[54:57], v[30:33]
	s_waitcnt lgkmcnt(1)
	v_mfma_f32_16x16x32_bf16 v[26:29], v[50:53], v[54:57], v[26:29]
	s_waitcnt vmcnt(8) lgkmcnt(0)
	s_barrier
	ds_read_b128 v[54:57], v224
	v_mfma_f32_16x16x32_bf16 v[22:25], v[46:49], v[58:61], v[22:25]
	v_mfma_f32_16x16x32_bf16 v[18:21], v[50:53], v[58:61], v[18:21]
	ds_read_b128 v[58:61], v224 offset:1024
	v_mfma_f32_16x16x32_bf16 v[14:17], v[46:49], v[62:65], v[14:17]
	v_mfma_f32_16x16x32_bf16 v[10:13], v[50:53], v[62:65], v[10:13]
	ds_read_b128 v[62:65], v224 offset:2048
	v_mfma_f32_16x16x32_bf16 v[6:9], v[46:49], v[216:219], v[6:9]
	ds_read_b128 v[46:49], v225 offset:8192
	v_mfma_f32_16x16x32_bf16 v[2:5], v[50:53], v[216:219], v[2:5]
	ds_read_b128 v[50:53], v225 offset:9216
	ds_read_b128 v[216:219], v224 offset:3072
	s_add_i32 s10, s10, 1
	s_cmp_lg_u32 s10, 6
	s_cselect_b32 s10, s10, 0
	s_lshl_b32 s94, s10, 14
	v_add_u32_e32 v226, s94, v38
	v_add_u32_e32 v225, v226, v40
	v_add_u32_e32 v224, v226, v39
	s_waitcnt lgkmcnt(2)
	v_mfma_f32_16x16x32_bf16 v[30:33], v[46:49], v[54:57], v[30:33]
	s_waitcnt lgkmcnt(1)
	v_mfma_f32_16x16x32_bf16 v[26:29], v[50:53], v[54:57], v[26:29]
	s_waitcnt vmcnt(4) lgkmcnt(0)
	s_barrier
	ds_read_b128 v[54:57], v224
	v_mfma_f32_16x16x32_bf16 v[22:25], v[46:49], v[58:61], v[22:25]
	v_mfma_f32_16x16x32_bf16 v[18:21], v[50:53], v[58:61], v[18:21]
	ds_read_b128 v[58:61], v224 offset:1024
	v_mfma_f32_16x16x32_bf16 v[14:17], v[46:49], v[62:65], v[14:17]
	v_mfma_f32_16x16x32_bf16 v[10:13], v[50:53], v[62:65], v[10:13]
	ds_read_b128 v[62:65], v224 offset:2048
	v_mfma_f32_16x16x32_bf16 v[6:9], v[46:49], v[216:219], v[6:9]
	ds_read_b128 v[46:49], v225 offset:8192
	v_mfma_f32_16x16x32_bf16 v[2:5], v[50:53], v[216:219], v[2:5]
	ds_read_b128 v[50:53], v225 offset:9216
	ds_read_b128 v[216:219], v224 offset:3072
	s_add_i32 s10, s10, 1
	s_cmp_lg_u32 s10, 6
	s_cselect_b32 s10, s10, 0
	s_lshl_b32 s94, s10, 14
	v_add_u32_e32 v226, s94, v38
	v_add_u32_e32 v225, v226, v40
	v_add_u32_e32 v224, v226, v39
	s_waitcnt lgkmcnt(2)
	v_mfma_f32_16x16x32_bf16 v[30:33], v[46:49], v[54:57], v[30:33]
	s_waitcnt lgkmcnt(1)
	v_mfma_f32_16x16x32_bf16 v[26:29], v[50:53], v[54:57], v[26:29]
	s_waitcnt vmcnt(0) lgkmcnt(0)
	s_barrier
; template <int N> DI void wait_vm() { asm volatile("s_waitcnt vmcnt(%0)" ::"n"(N) : "memory"); }
; DI void raw_barrier() { asm volatile("" ::: "memory"); __builtin_amdgcn_s_barrier(); asm volatile("" ::: "memory"); }
;     ...
;     __syncthreads();
; #pragma unroll
;     for (int d = 0; d < D; ++d) issue(d, d);
;     int cb = 0, ib = D;
;     for (int kt = 0; kt < KT; ++kt) {
;         if (D > 1 && kt + D - 1 < KT) wait_vm<(D - 1) * NIT>(); else wait_vm<0>();
;         raw_barrier();
;         compute(cb, kt + D < KT, kt + D, ib);
;         cb = (cb + 1 == NST) ? 0 : cb + 1;
;         ib = (ib + 1 == NST) ? 0 : ib + 1;
	ds_read_b128 v[54:57], v224
	v_mfma_f32_16x16x32_bf16 v[22:25], v[46:49], v[58:61], v[22:25]
	v_mfma_f32_16x16x32_bf16 v[18:21], v[50:53], v[58:61], v[18:21]
	ds_read_b128 v[58:61], v224 offset:1024
	v_mfma_f32_16x16x32_bf16 v[14:17], v[46:49], v[62:65], v[14:17]
	v_mfma_f32_16x16x32_bf16 v[10:13], v[50:53], v[62:65], v[10:13]
	ds_read_b128 v[62:65], v224 offset:2048
	v_mfma_f32_16x16x32_bf16 v[6:9], v[46:49], v[216:219], v[6:9]
	ds_read_b128 v[46:49], v225 offset:8192
	v_mfma_f32_16x16x32_bf16 v[2:5], v[50:53], v[216:219], v[2:5]
	ds_read_b128 v[50:53], v225 offset:9216
	ds_read_b128 v[216:219], v224 offset:3072
	s_add_i32 s10, s10, 1
	s_cmp_lg_u32 s10, 6
	s_cselect_b32 s10, s10, 0
	s_waitcnt lgkmcnt(2)
	v_mfma_f32_16x16x32_bf16 v[30:33], v[46:49], v[54:57], v[30:33]
	s_waitcnt lgkmcnt(1)
	v_mfma_f32_16x16x32_bf16 v[26:29], v[50:53], v[54:57], v[26:29]
	s_waitcnt lgkmcnt(0)
	v_mfma_f32_16x16x32_bf16 v[22:25], v[46:49], v[58:61], v[22:25]
	v_mfma_f32_16x16x32_bf16 v[18:21], v[50:53], v[58:61], v[18:21]
	v_mfma_f32_16x16x32_bf16 v[14:17], v[46:49], v[62:65], v[14:17]
	v_mfma_f32_16x16x32_bf16 v[10:13], v[50:53], v[62:65], v[10:13]
	v_mfma_f32_16x16x32_bf16 v[6:9], v[46:49], v[216:219], v[6:9]
	v_mfma_f32_16x16x32_bf16 v[2:5], v[50:53], v[216:219], v[2:5]
	s_branch .Lpkv_join
.Lpkv_c_entry:
	s_mov_b32 s7, 12
	s_mov_b32 s10, 1
	s_waitcnt vmcnt(2)
	s_barrier
	v_add_u32_e32 v225, v38, v40
	v_add_u32_e32 v224, v38, v39
	ds_read_b128 v[54:57], v224
	ds_read_b128 v[58:61], v224 offset:1024
	ds_read_b128 v[62:65], v224 offset:2048
	ds_read_b128 v[46:49], v225 offset:8192
	ds_read_b128 v[50:53], v225 offset:9216
	ds_read_b128 v[216:219], v224 offset:3072
; DI f32x4 mfma16(bf16x8 a, bf16x8 b, f32x4 c) { return __builtin_amdgcn_mfma_f32_16x16x32_bf16(a, b, c, 0, 0, 0); }
; template <int N> DI void wait_vm() { asm volatile("s_waitcnt vmcnt(%0)" ::"n"(N) : "memory"); }
; DI void raw_barrier() { asm volatile("" ::: "memory"); __builtin_amdgcn_s_barrier(); asm volatile("" ::: "memory"); }
;     ...
;     auto compute = [&](int cb, bool do_issue, int ikt, int ib) {
;         const char* base = lds + cb * BUF;
;         bf16x8 af[MT], bfr[NT];
; #pragma unroll
;         for (int nt = 0; nt < NT; ++nt) {
;             const int br = BM + (nt / NTS) * (BN / NSEG) + wc * (NTS * 16) + (nt % NTS) * 16;
;             bfr[nt] = *(const bf16x8*)(base + (br + l15) * 64 + rsw);
;         }
; #pragma unroll
;         for (int mt = 0; mt < MT; ++mt) af[mt] = *(const bf16x8*)(base + (wr * WM + mt * 16 + l15) * 64 + rsw);
;         constexpr int TOT = MT * NT, PER = (TOT + NIT - 1) / NIT;
; #pragma unroll
;         for (int part = 0; part < NIT; ++part) {
; #pragma unroll
;             for (int q = 0; q < PER; ++q) {
;                 const int idx = part * PER + q;
;                 if (idx < TOT) {
;                     const int mt = idx / NT, nt = idx % NT;
;                     acc[mt][nt] = SWAP ? mfma16(bfr[nt], af[mt], acc[mt][nt]) : mfma16(af[mt], bfr[nt], acc[mt][nt]);
;                 }
;             }
;             __builtin_amdgcn_sched_barrier(0);
;             if (do_issue) issue_one(ikt, ib, part);
;             __builtin_amdgcn_sched_barrier(0);
;         }
;     };
;     __syncthreads();
; #pragma unroll
;     for (int d = 0; d < D; ++d) issue(d, d);
;     int cb = 0, ib = D;
;     for (int kt = 0; kt < KT; ++kt) {
;         if (D > 1 && kt + D - 1 < KT) wait_vm<(D - 1) * NIT>(); else wait_vm<0>();
;         raw_barrier();
;         compute(cb, kt + D < KT, kt + D, ib);
;         cb = (cb + 1 == NST) ? 0 : cb + 1;
;         ib = (ib + 1 == NST) ? 0 : ib + 1;
;     }
.Lpkv_c_loop:
	s_lshl_b32 s94, s10, 14
	v_add_u32_e32 v226, s94, v38
	v_add_u32_e32 v225, v226, v40
	v_add_u32_e32 v224, v226, v39
	s_waitcnt lgkmcnt(2)
	v_mfma_f32_16x16x32_bf16 v[30:33], v[46:49], v[54:57], v[30:33]
	s_waitcnt lgkmcnt(1)
	v_mfma_f32_16x16x32_bf16 v[26:29], v[50:53], v[54:57], v[26:29]
	s_waitcnt vmcnt(0) lgkmcnt(0)
	s_barrier
	ds_read_b128 v[54:57], v224
	v_mfma_f32_16x16x32_bf16 v[22:25], v[46:49], v[58:61], v[22:25]
	v_mfma_f32_16x16x32_bf16 v[18:21], v[50:53], v[58:61], v[18:21]
	ds_read_b128 v[58:61], v224 offset:1024
	v_mfma_f32_16x16x32_bf16 v[14:17], v[46:49], v[62:65], v[14:17]
	v_mfma_f32_16x16x32_bf16 v[10:13], v[50:53], v[62:65], v[10:13]
	ds_read_b128 v[62:65], v224 offset:2048
	v_mfma_f32_16x16x32_bf16 v[6:9], v[46:49], v[216:219], v[6:9]
	ds_read_b128 v[46:49], v225 offset:8192
	v_mfma_f32_16x16x32_bf16 v[2:5], v[50:53], v[216:219], v[2:5]
	ds_read_b128 v[50:53], v225 offset:9216
	ds_read_b128 v[216:219], v224 offset:3072
	s_add_i32 s10, s10, 1
	s_cmp_lg_u32 s10, 6
	s_cselect_b32 s10, s10, 0
	s_add_i32 s7, s7, 2
	s_cmp_lg_u32 s7, 64
	s_cbranch_scc1 .Lpkv_c_loop
	s_lshl_b32 s94, s10, 14
	v_add_u32_e32 v226, s94, v38
	v_add_u32_e32 v225, v226, v40
	v_add_u32_e32 v224, v226, v39
	s_waitcnt lgkmcnt(2)
	v_mfma_f32_16x16x32_bf16 v[30:33], v[46:49], v[54:57], v[30:33]
	s_waitcnt lgkmcnt(1)
	v_mfma_f32_16x16x32_bf16 v[26:29], v[50:53], v[54:57], v[26:29]
	s_waitcnt vmcnt(0) lgkmcnt(0)
	s_barrier
	ds_read_b128 v[54:57], v224
	v_mfma_f32_16x16x32_bf16 v[22:25], v[46:49], v[58:61], v[22:25]
	v_mfma_f32_16x16x32_bf16 v[18:21], v[50:53], v[58:61], v[18:21]
	ds_read_b128 v[58:61], v224 offset:1024
	v_mfma_f32_16x16x32_bf16 v[14:17], v[46:49], v[62:65], v[14:17]
	v_mfma_f32_16x16x32_bf16 v[10:13], v[50:53], v[62:65], v[10:13]
	ds_read_b128 v[62:65], v224 offset:2048
	v_mfma_f32_16x16x32_bf16 v[6:9], v[46:49], v[216:219], v[6:9]
	ds_read_b128 v[46:49], v225 offset:8192
	v_mfma_f32_16x16x32_bf16 v[2:5], v[50:53], v[216:219], v[2:5]
	ds_read_b128 v[50:53], v225 offset:9216
	ds_read_b128 v[216:219], v224 offset:3072
	s_add_i32 s10, s10, 1
	s_cmp_lg_u32 s10, 6
	s_cselect_b32 s10, s10, 0
	s_lshl_b32 s94, s10, 14
	v_add_u32_e32 v226, s94, v38
	v_add_u32_e32 v225, v226, v40
	v_add_u32_e32 v224, v226, v39
	s_waitcnt lgkmcnt(2)
	v_mfma_f32_16x16x32_bf16 v[30:33], v[46:49], v[54:57], v[30:33]
	s_waitcnt lgkmcnt(1)
	v_mfma_f32_16x16x32_bf16 v[26:29], v[50:53], v[54:57], v[26:29]
	s_waitcnt vmcnt(0) lgkmcnt(0)
	s_barrier
	ds_read_b128 v[54:57], v224
	v_mfma_f32_16x16x32_bf16 v[22:25], v[46:49], v[58:61], v[22:25]
	v_mfma_f32_16x16x32_bf16 v[18:21], v[50:53], v[58:61], v[18:21]
	ds_read_b128 v[58:61], v224 offset:1024
	v_mfma_f32_16x16x32_bf16 v[14:17], v[46:49], v[62:65], v[14:17]
	v_mfma_f32_16x16x32_bf16 v[10:13], v[50:53], v[62:65], v[10:13]
	ds_read_b128 v[62:65], v224 offset:2048
	v_mfma_f32_16x16x32_bf16 v[6:9], v[46:49], v[216:219], v[6:9]
	ds_read_b128 v[46:49], v225 offset:8192
	v_mfma_f32_16x16x32_bf16 v[2:5], v[50:53], v[216:219], v[2:5]
	ds_read_b128 v[50:53], v225 offset:9216
	ds_read_b128 v[216:219], v224 offset:3072
	s_add_i32 s10, s10, 1
	s_cmp_lg_u32 s10, 6
	s_cselect_b32 s10, s10, 0
	s_lshl_b32 s94, s10, 14
	v_add_u32_e32 v226, s94, v38
	v_add_u32_e32 v225, v226, v40
	v_add_u32_e32 v224, v226, v39
	s_waitcnt lgkmcnt(2)
	v_mfma_f32_16x16x32_bf16 v[30:33], v[46:49], v[54:57], v[30:33]
	s_waitcnt lgkmcnt(1)
	v_mfma_f32_16x16x32_bf16 v[26:29], v[50:53], v[54:57], v[26:29]
	s_waitcnt vmcnt(0) lgkmcnt(0)
	s_barrier
	ds_read_b128 v[54:57], v224
	v_mfma_f32_16x16x32_bf16 v[22:25], v[46:49], v[58:61], v[22:25]
	v_mfma_f32_16x16x32_bf16 v[18:21], v[50:53], v[58:61], v[18:21]
	ds_read_b128 v[58:61], v224 offset:1024
	v_mfma_f32_16x16x32_bf16 v[14:17], v[46:49], v[62:65], v[14:17]
	v_mfma_f32_16x16x32_bf16 v[10:13], v[50:53], v[62:65], v[10:13]
	ds_read_b128 v[62:65], v224 offset:2048
	v_mfma_f32_16x16x32_bf16 v[6:9], v[46:49], v[216:219], v[6:9]
	ds_read_b128 v[46:49], v225 offset:8192
	v_mfma_f32_16x16x32_bf16 v[2:5], v[50:53], v[216:219], v[2:5]
	ds_read_b128 v[50:53], v225 offset:9216
	ds_read_b128 v[216:219], v224 offset:3072
	s_add_i32 s10, s10, 1
	s_cmp_lg_u32 s10, 6
	s_cselect_b32 s10, s10, 0
	s_lshl_b32 s94, s10, 14
	v_add_u32_e32 v226, s94, v38
	v_add_u32_e32 v225, v226, v40
	v_add_u32_e32 v224, v226, v39
	s_waitcnt lgkmcnt(2)
	v_mfma_f32_16x16x32_bf16 v[30:33], v[46:49], v[54:57], v[30:33]
	s_waitcnt lgkmcnt(1)
	v_mfma_f32_16x16x32_bf16 v[26:29], v[50:53], v[54:57], v[26:29]
	s_waitcnt vmcnt(0) lgkmcnt(0)
	s_barrier
	ds_read_b128 v[54:57], v224
	v_mfma_f32_16x16x32_bf16 v[22:25], v[46:49], v[58:61], v[22:25]
	v_mfma_f32_16x16x32_bf16 v[18:21], v[50:53], v[58:61], v[18:21]
	ds_read_b128 v[58:61], v224 offset:1024
	v_mfma_f32_16x16x32_bf16 v[14:17], v[46:49], v[62:65], v[14:17]
	v_mfma_f32_16x16x32_bf16 v[10:13], v[50:53], v[62:65], v[10:13]
	ds_read_b128 v[62:65], v224 offset:2048
	v_mfma_f32_16x16x32_bf16 v[6:9], v[46:49], v[216:219], v[6:9]
	ds_read_b128 v[46:49], v225 offset:8192
	v_mfma_f32_16x16x32_bf16 v[2:5], v[50:53], v[216:219], v[2:5]
	ds_read_b128 v[50:53], v225 offset:9216
	ds_read_b128 v[216:219], v224 offset:3072
	s_add_i32 s10, s10, 1
	s_cmp_lg_u32 s10, 6
	s_cselect_b32 s10, s10, 0
	s_lshl_b32 s94, s10, 14
	v_add_u32_e32 v226, s94, v38
	v_add_u32_e32 v225, v226, v40
	v_add_u32_e32 v224, v226, v39
	s_waitcnt lgkmcnt(2)
	v_mfma_f32_16x16x32_bf16 v[30:33], v[46:49], v[54:57], v[30:33]
	s_waitcnt lgkmcnt(1)
	v_mfma_f32_16x16x32_bf16 v[26:29], v[50:53], v[54:57], v[26:29]
	s_waitcnt vmcnt(0) lgkmcnt(0)
	s_barrier
	ds_read_b128 v[54:57], v224
	v_mfma_f32_16x16x32_bf16 v[22:25], v[46:49], v[58:61], v[22:25]
	v_mfma_f32_16x16x32_bf16 v[18:21], v[50:53], v[58:61], v[18:21]
	ds_read_b128 v[58:61], v224 offset:1024
	v_mfma_f32_16x16x32_bf16 v[14:17], v[46:49], v[62:65], v[14:17]
	v_mfma_f32_16x16x32_bf16 v[10:13], v[50:53], v[62:65], v[10:13]
	ds_read_b128 v[62:65], v224 offset:2048
	v_mfma_f32_16x16x32_bf16 v[6:9], v[46:49], v[216:219], v[6:9]
	ds_read_b128 v[46:49], v225 offset:8192
	v_mfma_f32_16x16x32_bf16 v[2:5], v[50:53], v[216:219], v[2:5]
	ds_read_b128 v[50:53], v225 offset:9216
	ds_read_b128 v[216:219], v224 offset:3072
	s_add_i32 s10, s10, 1
	s_cmp_lg_u32 s10, 6
	s_cselect_b32 s10, s10, 0
	s_waitcnt lgkmcnt(2)
	v_mfma_f32_16x16x32_bf16 v[30:33], v[46:49], v[54:57], v[30:33]
	s_waitcnt lgkmcnt(1)
	v_mfma_f32_16x16x32_bf16 v[26:29], v[50:53], v[54:57], v[26:29]
	s_waitcnt lgkmcnt(0)
	v_mfma_f32_16x16x32_bf16 v[22:25], v[46:49], v[58:61], v[22:25]
	v_mfma_f32_16x16x32_bf16 v[18:21], v[50:53], v[58:61], v[18:21]
	v_mfma_f32_16x16x32_bf16 v[14:17], v[46:49], v[62:65], v[14:17]
	v_mfma_f32_16x16x32_bf16 v[10:13], v[50:53], v[62:65], v[10:13]
	v_mfma_f32_16x16x32_bf16 v[6:9], v[46:49], v[216:219], v[6:9]
	v_mfma_f32_16x16x32_bf16 v[2:5], v[50:53], v[216:219], v[2:5]
